# attention phases (MLA, SWA): one static s_setprio 1 for waves 4-7 at phase entry instead of per-tile s_setprio 1/0 flips around the score MFMAs
# speedup vs baseline: 1.0059x; 1.0032x over previous
; template <bool MLA>
; __device__ __forceinline__ void attn_phase(const Args& a, LAS unsigned char* lds) {
;     ...
; #pragma unroll 1
;     for (int item = bidx(); item < NITEM; item += gridDim.x) {
;         const bool samp = item >= NP;
;         int b, h = 0, kvh = 0, cch = 0, p4 = 0;
;         size_t qrow0, krow0 = 0; int kt0 = 0, kt1, nq;
;         if (MLA) {
;             if (!samp) { p4 = 7 - (item >> 9); const int bh = item & 511; b = bh >> 4; h = bh & 15; qrow0 = (size_t)b * 2048 + p4 * 256; krow0 = (size_t)b * 2048; kt1 = 4 * p4 + 4; nq = 256; }
;             else { const int it = item - NP; b = it >> 4; h = it & 15; qrow0 = (size_t)NTP + b * 32; krow0 = (size_t)NTP + (size_t)b * 1056; kt1 = 17; nq = 32; }
;         } else {
;             if (!samp) { b = item >> 7; cch = (item >> 2) & 31; kvh = item & 3; qrow0 = (size_t)b * 2048 + cch * 64; kt0 = cch >= 2 ? 0 : 2 - cch; kt1 = 3; nq = 256; }
;             else { const int it = item - NP; b = it >> 2; kvh = it & 3; qrow0 = (size_t)NTP + b * 32; kt1 = 3; nq = 128; }
;         }
;         int head, nkw, qi[2]; bool qvalid[2];
;         if (MLA) { head = h; nkw = samp ? 1056 : (4 * p4 + (w >> 1) + 1) * 64;
; #pragma unroll
;             for (int g = 0; g < 2; ++g) { qi[g] = w * 32 + g * 16 + r; qvalid[g] = qi[g] < nq; } }
;         else if (!samp) { head = kvh * 4 + (w >> 1); nkw = 192;
; #pragma unroll
;             for (int g = 0; g < 2; ++g) { qi[g] = (w & 1) * 32 + g * 16 + r; qvalid[g] = true; } }
;         else { head = kvh * 4 + (w & 3); nkw = 160;
; #pragma unroll
;             for (int g = 0; g < 2; ++g) { qi[g] = g * 16 + r; qvalid[g] = w < 4; } }
;     ...
;         auto fetch = [&](int kt) {
;             pk0 = (u32x4){0u, 0u, 0u, 0u}; pk1 = pk0; pv = pk0;
;             if (MLA) {
;                 { const int j = tid / 12, ch = tid % 12; const int kk = kt * 64 + j; const size_t kr = krow0 + kk;
;                   if (!samp || kk < 1056) pk0 = ch < 8 ? *(const u32x4*)(KVg + kr * 2048 + h * 128 + ch * 8) : *(const u32x4*)(KRg + kr * 32 + (ch - 8) * 8); }
;                 if (tid < 256) { const int idx = tid + 512; const int j = idx / 12, ch = idx % 12; const int kk = kt * 64 + j; const size_t kr = krow0 + kk;
;                   if (!samp || kk < 1056) pk1 = ch < 8 ? *(const u32x4*)(KVg + kr * 2048 + h * 128 + ch * 8) : *(const u32x4*)(KRg + kr * 32 + (ch - 8) * 8); }
.LBB0_439:
	s_or_b64 exec, exec, s[0:1]
	v_mov_b32_e32 v107, v187
	s_mov_b32 s33, s69
	s_waitcnt lgkmcnt(0)
	s_barrier
	v_readfirstlane_b32 s0, v187
	s_cmp_lt_u32 s0, 0x100
	s_cbranch_scc1 .Lprio_mla_lo
	s_setprio 1
.Lprio_mla_lo:
	s_cmpk_gt_i32 s33, 0x10ff
	v_readfirstlane_b32 s0, v107
	s_cbranch_scc1 .LBB0_509
	s_ashr_i32 s0, s0, 1
	v_and_b32_e32 v3, 15, v107
	s_and_b32 s61, s0, 0xffffffc0
	s_andn2_b32 s0, s0, 31
	v_or_b32_e32 v88, s0, v3
	s_movk_i32 s0, 0x800
	v_lshlrev_b32_e32 v157, 3, v107
	v_cmp_gt_i32_e64 s[36:37], s0, v107
	v_and_b32_e32 v2, 8, v157
	v_readlane_b32 s0, v252, 18
	v_ashrrev_i32_e32 v156, 1, v107
	v_lshlrev_b32_e32 v0, 3, v2
	v_readlane_b32 s1, v252, 19
	s_movk_i32 s4, 0xd0
	v_lshlrev_b32_e32 v5, 1, v2
	v_lshl_add_u64 v[90:91], s[0:1], 0, v[0:1]
	v_mul_lo_u32 v0, v156, s4
	s_mov_b32 s1, 0x2aaaaaab
	v_add3_u32 v158, 0, v0, v5
	v_mul_hi_i32 v0, v107, s1
	v_lshrrev_b32_e32 v5, 31, v0
	v_ashrrev_i32_e32 v0, 1, v0
	v_add_u32_e32 v92, v0, v5
	v_mul_lo_u32 v0, v92, 12
	v_sub_u32_e32 v5, v107, v0
	v_readlane_b32 s2, v253, 14
	v_lshlrev_b32_e32 v0, 3, v5
	v_readlane_b32 s3, v253, 15
	v_ashrrev_i32_e32 v97, 31, v0
	v_mov_b32_e32 v96, v0
	v_lshl_add_u64 v[94:95], v[0:1], 1, s[2:3]
	v_add_u32_e32 v0, 0x200, v107
	v_mul_hi_i32 v6, v0, s1
	v_lshrrev_b32_e32 v7, 31, v6
	v_ashrrev_i32_e32 v6, 1, v6
	v_add_u32_e32 v98, v6, v7
	s_movk_i32 s0, 0x317f
	v_mul_lo_u32 v6, v98, 12
	v_cmp_lt_i32_e64 s[38:39], s0, v107
	s_movk_i32 s0, 0x100
	v_sub_u32_e32 v6, v0, v6
	v_cmp_gt_i32_e64 s[44:45], s0, v107
	v_lshlrev_b32_e32 v0, 3, v6
	v_ashrrev_i32_e32 v104, 3, v107
	s_movk_i32 s0, 0x41f
	v_and_b32_e32 v106, 56, v157
	v_lshl_add_u64 v[100:101], v[0:1], 1, s[2:3]
	v_ashrrev_i32_e32 v103, 31, v0
	v_mov_b32_e32 v102, v0
	v_cmp_lt_i32_e64 s[50:51], s0, v104
	v_mul_u32_u24_e32 v163, 0x88, v106
	v_lshlrev_b32_e32 v0, 1, v104
	v_readlane_b32 s0, v254, 22
	v_bfe_u32 v4, v107, 4, 2
	v_mul_lo_u32 v159, v92, s4
	v_add3_u32 v164, s0, v163, v0
	v_xor_b32_e32 v0, 16, v234
	v_cmp_lt_i32_e32 vcc, v0, v235
	s_movk_i32 s0, 0x2e7f
	v_cmp_lt_i32_e64 s[52:53], s0, v107
	v_cndmask_b32_e32 v0, v234, v0, vcc
	v_lshlrev_b32_e32 v167, 2, v0
	v_xor_b32_e32 v0, 32, v234
	s_movk_i32 s0, 0x3df
	v_cmp_lt_i32_e32 vcc, v0, v235
	v_mul_lo_u32 v161, v98, s4
	v_cmp_lt_i32_e64 s[54:55], s0, v104
	v_readlane_b32 s2, v253, 24
	v_lshlrev_b32_e32 v165, 4, v4
	v_cndmask_b32_e32 v0, v234, v0, vcc
	v_readlane_b32 s0, v252, 20
	v_cmp_gt_i32_e64 s[40:41], 8, v5
	v_cmp_lt_i32_e64 s[42:43], 7, v5
	v_cmp_gt_i32_e64 s[46:47], 8, v6
	v_cmp_lt_i32_e64 s[48:49], 7, v6
	v_add_u32_e32 v7, 0, v159
	v_lshlrev_b32_e32 v160, 4, v5
	v_add_u32_e32 v5, 0, v161
	v_lshlrev_b32_e32 v162, 4, v6
	v_add_u32_e32 v108, 64, v92
	v_add_u32_e32 v110, 64, v98
	v_add_u32_e32 v112, 64, v104
	v_readlane_b32 s3, v253, 25
	v_add_u32_e32 v6, 0, v165
	v_lshlrev_b32_e32 v166, 2, v4
	v_lshlrev_b32_e32 v118, 3, v4
	v_lshlrev_b32_e32 v168, 2, v0
	v_mov_b32_e32 v119, v1
	v_readlane_b32 s1, v252, 21
	v_or_b32_e32 v122, 16, v88
	v_mul_lo_u32 v4, v88, s4
	v_lshlrev_b32_e32 v0, 1, v106
	s_add_i32 s61, s61, 64
	v_ashrrev_i32_e32 v93, 31, v92
	v_ashrrev_i32_e32 v99, 31, v98
	v_ashrrev_i32_e32 v105, 31, v104
	v_ashrrev_i32_e32 v109, 31, v108
	v_ashrrev_i32_e32 v111, 31, v110
	v_ashrrev_i32_e32 v113, 31, v112
	v_lshl_add_u64 v[114:115], v[96:97], 1, s[2:3]
	v_lshl_add_u64 v[116:117], v[102:103], 1, s[2:3]
	v_lshl_add_u64 v[120:121], s[0:1], 0, v[118:119]
	v_mul_u32_u24_e32 v119, 0xd0, v3
	v_mul_u32_u24_e32 v169, 0x88, v3
	v_ashrrev_i32_e32 v89, 31, v88
	v_ashrrev_i32_e32 v123, 31, v122
	v_lshl_add_u64 v[124:125], s[2:3], 0, v[0:1]
	v_lshlrev_b32_e32 v126, 1, v2
	v_add_u32_e32 v170, v7, v160
	v_add_u32_e32 v171, v5, v162
	v_add_u32_e32 v172, v6, v4
	s_branch .LBB0_442

; #define LAS __attribute__((address_space(3)))
; template <bool MLA>
; __device__ __forceinline__ void attn_phase(const Args& a, LAS unsigned char* lds) {
;     ...
;             f32x4 s[2][4];
;             __builtin_amdgcn_s_setprio(1);
; #pragma unroll
;             for (int sub = 0; sub < 4; ++sub) {
;                 f32x4 a0 = (f32x4){0.f, 0.f, 0.f, 0.f}, a1 = a0;
; #pragma unroll
;                 for (int ks = 0; ks < NKS; ++ks) {
;                     const bf16x8 kf = *(const LAS bf16x8*)(Ks + (sub * 16 + r) * QST + ks * 32 + quad * 8);
;                     a0 = __builtin_amdgcn_mfma_f32_16x16x32_bf16(kf, qf[0][ks], a0, 0, 0, 0);
;                     a1 = __builtin_amdgcn_mfma_f32_16x16x32_bf16(kf, qf[1][ks], a1, 0, 0, 0);
;                 }
;                 s[0][sub] = a0; s[1][sub] = a1;
;             }
;             __builtin_amdgcn_s_setprio(0);
;             bf16x8 pf[2][2];
;             const bool need_mask = kt * 64 + 64 > nkw;
; #pragma unroll
;             for (int g = 0; g < 2; ++g) {
;                 f32x4 sv[4];
; #pragma unroll
;                 for (int sub = 0; sub < 4; ++sub) sv[sub] = s[g][sub] * scale;
;                 if (!MLA) {
; #pragma unroll
;                     for (int sub = 0; sub < 4; ++sub)
; #pragma unroll
;                         for (int jj = 0; jj < 4; ++jj) sv[sub][jj] += biasT[head * 256 + 191 + qi[g] - (kt * 64 + sub * 16 + quad * 4 + jj)];
;                 }
;                 if (need_mask) {
; #pragma unroll
;                     for (int sub = 0; sub < 4; ++sub)
; #pragma unroll
;                         for (int jj = 0; jj < 4; ++jj) if (kt * 64 + sub * 16 + quad * 4 + jj >= nkw) sv[sub][jj] = -INFINITY;
;                 }
.LBB0_497:
	s_bitcmp1_b32 s6, 0
	s_cselect_b32 s0, 0x5600, 0
	s_add_i32 s68, s0, 0
	v_add3_u32 v0, s68, v165, v119
	ds_read_b128 v[208:211], v0 offset:53248
	ds_read_b128 v[212:215], v0 offset:53312
	ds_read_b128 v[216:219], v0 offset:53376
	ds_read_b128 v[220:223], v0 offset:56576
	ds_read_b128 v[224:227], v0 offset:56640
	ds_read_b128 v[228:231], v0 offset:56704
	s_waitcnt lgkmcnt(5)
	v_mfma_f32_16x16x32_bf16 v[134:137], v[208:211], v[24:27], 0
	v_mfma_f32_16x16x32_bf16 v[72:75], v[208:211], v[12:15], 0
	s_waitcnt lgkmcnt(4)
	v_mfma_f32_16x16x32_bf16 v[134:137], v[212:215], v[20:23], v[134:137]
	v_mfma_f32_16x16x32_bf16 v[72:75], v[212:215], v[8:11], v[72:75]
	s_waitcnt lgkmcnt(3)
	v_mfma_f32_16x16x32_bf16 v[134:137], v[216:219], v[16:19], v[134:137]
	v_mfma_f32_16x16x32_bf16 v[72:75], v[216:219], v[4:7], v[72:75]
	ds_read_b128 v[208:211], v0 offset:59904
	ds_read_b128 v[212:215], v0 offset:59968
	ds_read_b128 v[216:219], v0 offset:60032
	s_waitcnt lgkmcnt(5)
	v_mfma_f32_16x16x32_bf16 v[150:153], v[220:223], v[24:27], 0
	v_mfma_f32_16x16x32_bf16 v[76:79], v[220:223], v[12:15], 0
	s_waitcnt lgkmcnt(4)
	v_mfma_f32_16x16x32_bf16 v[150:153], v[224:227], v[20:23], v[150:153]
	v_mfma_f32_16x16x32_bf16 v[76:79], v[224:227], v[8:11], v[76:79]
	s_waitcnt lgkmcnt(3)
	v_mfma_f32_16x16x32_bf16 v[150:153], v[228:231], v[16:19], v[150:153]
	v_mfma_f32_16x16x32_bf16 v[76:79], v[228:231], v[4:7], v[76:79]
	ds_read_b128 v[220:223], v0 offset:63232
	ds_read_b128 v[224:227], v0 offset:63296
	ds_read_b128 v[228:231], v0 offset:63360
	s_waitcnt lgkmcnt(5)
	v_mfma_f32_16x16x32_bf16 v[146:149], v[208:211], v[24:27], 0
	v_mfma_f32_16x16x32_bf16 v[80:83], v[208:211], v[12:15], 0
	s_waitcnt lgkmcnt(4)
	v_mfma_f32_16x16x32_bf16 v[146:149], v[212:215], v[20:23], v[146:149]
	v_mfma_f32_16x16x32_bf16 v[80:83], v[212:215], v[8:11], v[80:83]
	s_waitcnt lgkmcnt(3)
	v_mfma_f32_16x16x32_bf16 v[146:149], v[216:219], v[16:19], v[146:149]
	v_mfma_f32_16x16x32_bf16 v[80:83], v[216:219], v[4:7], v[80:83]
	s_waitcnt lgkmcnt(2)
	v_mfma_f32_16x16x32_bf16 v[138:141], v[220:223], v[24:27], 0
	v_mfma_f32_16x16x32_bf16 v[84:87], v[220:223], v[12:15], 0
	s_waitcnt lgkmcnt(1)
	v_mfma_f32_16x16x32_bf16 v[138:141], v[224:227], v[20:23], v[138:141]
	v_mfma_f32_16x16x32_bf16 v[84:87], v[224:227], v[8:11], v[84:87]
	s_waitcnt lgkmcnt(0)
	v_mfma_f32_16x16x32_bf16 v[138:141], v[228:231], v[16:19], v[138:141]
	v_mfma_f32_16x16x32_bf16 v[84:87], v[228:231], v[4:7], v[84:87]
	v_add_u32_e32 v2, s66, v166
	s_cmp_gt_i32 s66, s65
	v_subrev_u32_e32 v0, 64, v2
	s_mov_b32 s0, 0x3e16c740
	v_subrev_u32_e32 v176, 63, v2
	v_subrev_u32_e32 v177, 62, v2
	v_subrev_u32_e32 v178, 61, v2
	v_subrev_u32_e32 v179, 48, v2
	v_subrev_u32_e32 v180, 47, v2
	v_subrev_u32_e32 v181, 46, v2
	v_subrev_u32_e32 v182, 45, v2
	v_subrev_u32_e32 v183, 32, v2
	v_subrev_u32_e32 v184, 31, v2
	v_subrev_u32_e32 v185, 30, v2
	v_subrev_u32_e32 v197, 29, v2
	v_add_u32_e32 v202, -16, v2
	v_add_u32_e32 v203, -15, v2
	v_add_u32_e32 v204, -14, v2
	v_add_u32_e32 v205, -13, v2
	s_cselect_b64 s[58:59], -1, 0
	s_cmp_le_i32 s66, s65
	v_pk_mul_f32 v[140:141], v[140:141], s[0:1] op_sel_hi:[1,0]
	v_pk_mul_f32 v[144:145], v[148:149], s[0:1] op_sel_hi:[1,0]
	v_pk_mul_f32 v[148:149], v[152:153], s[0:1] op_sel_hi:[1,0]
	v_pk_mul_f32 v[152:153], v[136:137], s[0:1] op_sel_hi:[1,0]
	v_pk_mul_f32 v[142:143], v[138:139], s[0:1] op_sel_hi:[1,0]
	v_pk_mul_f32 v[146:147], v[146:147], s[0:1] op_sel_hi:[1,0]
	v_pk_mul_f32 v[150:151], v[150:151], s[0:1] op_sel_hi:[1,0]
	v_pk_mul_f32 v[154:155], v[134:135], s[0:1] op_sel_hi:[1,0]
	v_cmp_gt_i32_e32 vcc, s65, v0
	v_cmp_gt_i32_e64 s[0:1], s65, v176
	v_cmp_gt_i32_e64 s[2:3], s65, v177
	v_cmp_gt_i32_e64 s[4:5], s65, v178
	v_cmp_gt_i32_e64 s[6:7], s65, v179
	v_cmp_gt_i32_e64 s[10:11], s65, v180
	v_cmp_gt_i32_e64 s[12:13], s65, v181
	v_cmp_gt_i32_e64 s[14:15], s65, v182
	v_cmp_gt_i32_e64 s[16:17], s65, v183
	v_cmp_gt_i32_e64 s[18:19], s65, v184
	v_cmp_gt_i32_e64 s[20:21], s65, v185
	v_cmp_gt_i32_e64 s[22:23], s65, v197
	v_cmp_gt_i32_e64 s[24:25], s65, v202
	v_cmp_gt_i32_e64 s[26:27], s65, v203
	v_cmp_gt_i32_e64 s[28:29], s65, v204
	v_cmp_gt_i32_e64 s[8:9], s65, v205
	s_cbranch_scc1 .LBB0_499
	s_or_b64 s[28:29], s[8:9], s[28:29]
	s_or_b64 s[26:27], s[28:29], s[26:27]
	s_or_b64 s[24:25], s[26:27], s[24:25]
	s_or_b64 s[22:23], s[24:25], s[22:23]
	s_or_b64 s[20:21], s[22:23], s[20:21]
	s_or_b64 s[18:19], s[20:21], s[18:19]
	s_or_b64 s[16:17], s[18:19], s[16:17]
	s_or_b64 s[14:15], s[16:17], s[14:15]
	s_or_b64 s[12:13], s[14:15], s[12:13]
	s_or_b64 s[10:11], s[12:13], s[10:11]
	s_or_b64 s[6:7], s[10:11], s[6:7]
	s_or_b64 s[4:5], s[6:7], s[4:5]
	s_or_b64 s[2:3], s[4:5], s[2:3]
	s_or_b64 s[0:1], s[2:3], s[0:1]
	s_or_b64 vcc, s[0:1], vcc
	v_cndmask_b32_e64 v140, v245, v140, s[28:29]
	v_cndmask_b32_e64 v143, v245, v143, s[26:27]
	v_cndmask_b32_e64 v142, v245, v142, s[24:25]
	v_cndmask_b32_e64 v145, v245, v145, s[22:23]
	v_cndmask_b32_e64 v144, v245, v144, s[20:21]
	v_cndmask_b32_e64 v147, v245, v147, s[18:19]
	v_cndmask_b32_e64 v146, v245, v146, s[16:17]
	v_cndmask_b32_e64 v149, v245, v149, s[14:15]
	v_cndmask_b32_e64 v148, v245, v148, s[12:13]
	v_cndmask_b32_e64 v151, v245, v151, s[10:11]
	v_cndmask_b32_e64 v150, v245, v150, s[6:7]
	v_cndmask_b32_e64 v153, v245, v153, s[4:5]
	v_cndmask_b32_e64 v152, v245, v152, s[2:3]
	v_cndmask_b32_e64 v155, v245, v155, s[0:1]
	v_cndmask_b32_e32 v154, v245, v154, vcc
	v_cndmask_b32_e64 v141, v245, v141, s[8:9]

; __device__ __forceinline__ void xcd_barrier(const XcdBarrier& b) {
;     asm volatile("s_waitcnt vmcnt(0)" ::: "memory");
;     __syncthreads();
;     if (threadIdx.x == 0) {
;         unsigned* bar = b.bar;
;         __builtin_amdgcn_s_waitcnt(0);
;         unsigned nloc = b.st[0], nx = b.st[1];
;         if (nloc == 0u) { xcd_barrier_complete(bar, b.x, nloc, nx); b.st[0] = nloc; b.st[1] = nx; }
.LBB0_509:
	s_waitcnt vmcnt(0)
	s_waitcnt lgkmcnt(0)
	s_setprio 0
	s_barrier
	s_mov_b64 s[0:1], exec
	v_readlane_b32 s2, v251, 4
	v_readlane_b32 s3, v251, 5
	s_and_b64 s[2:3], s[0:1], s[2:3]
	s_mov_b64 exec, s[2:3]
	s_cbranch_execz .LBB0_561
	v_readlane_b32 s2, v254, 20
	s_waitcnt vmcnt(0) expcnt(0) lgkmcnt(0)
	s_nop 0
	v_mov_b32_e32 v0, s2
	ds_read_b32 v3, v0
	v_readlane_b32 s2, v254, 21
	s_waitcnt lgkmcnt(0)
	v_cmp_ne_u32_e32 vcc, 0, v3
	v_mov_b32_e32 v0, s2
	ds_read_b32 v2, v0
	s_cbranch_vccnz .LBB0_525
	s_mov_b32 s8, 1
	s_branch .LBB0_513

; __device__ __forceinline__ int tidx() { int t = threadIdx.x; OPAQUE_V(t); return t; }
; __device__ __forceinline__ int bidx() { int b = blockIdx.x; OPAQUE_S(b); return b; }
; __device__ __forceinline__ f32x4 bf4(const u32x2 t) { return (f32x4){__uint_as_float(t.x << 16), __uint_as_float(t.x & 0xFFFF0000u), __uint_as_float(t.y << 16), __uint_as_float(t.y & 0xFFFF0000u)}; }
; __device__ __forceinline__ void swa_state_out(const Args& a) {
;     const bf16_t* SP = (const bf16_t*)(a.ws + BS_PROJ);
;     const size_t gt = (size_t)bidx() * NTHREADS + tidx(), NGT = (size_t)gridDim.x * NTHREADS;
;     for (size_t i = gt; i < 32ull * 128 * 64; i += NGT) { const size_t b = i >> 13, j = (i >> 6) & 127; const int c = (int)(i & 63) * 4;
;         const size_t row = b * 2048 + 1920 + j;
;         const u32x2 k = *(const u32x2*)(SP + row * 1536 + 1024 + c), v = *(const u32x2*)(SP + row * 1536 + 1280 + c);
;         *(f32x4*)(a.out + O_SKP + i * 4) = bf4(k); *(f32x4*)(a.out + O_SVP + i * 4) = bf4(v); }
.LBB0_800:
	s_or_b64 exec, exec, s[0:1]
	s_mov_b32 s0, s69
	s_waitcnt lgkmcnt(0)
	s_barrier
	v_readfirstlane_b32 s1, v187
	s_cmp_lt_u32 s1, 0x100
	s_cbranch_scc1 .Lprio_swa_lo
	s_setprio 1
.Lprio_swa_lo:
	s_ashr_i32 s1, s0, 31
	v_mov_b32_e32 v4, v187
	s_lshl_b64 s[2:3], s[0:1], 9
	s_nop 0
	v_ashrrev_i32_e32 v5, 31, v4
	v_lshl_add_u64 v[2:3], s[2:3], 0, v[4:5]
	s_mov_b64 s[2:3], 0x40000
	v_cmp_gt_u64_e32 vcc, s[2:3], v[2:3]
	s_and_saveexec_b64 s[2:3], vcc
	v_readlane_b32 s8, v252, 10
	v_readlane_b32 s10, v253, 9
	v_readlane_b32 s9, v252, 11
	v_readlane_b32 s11, v253, 10
	s_movk_i32 s16, 0xc00
	s_cbranch_execz .LBB0_803
	s_lshl_b64 s[4:5], s[0:1], 13
	v_readlane_b32 s6, v254, 15
	s_add_u32 s4, s6, s4
	v_readlane_b32 s6, v254, 16
	s_addc_u32 s5, s6, s5
	v_lshl_add_u64 v[6:7], v[4:5], 4, s[4:5]
	s_lshl_b64 s[4:5], s[0:1], 11
	v_lshl_add_u64 v[8:9], v[4:5], 2, s[4:5]
	s_mov_b64 s[4:5], 0
	v_mov_b64_e32 v[10:11], v[2:3]

; #define LAS __attribute__((address_space(3)))
; template <bool MLA>
; __device__ __forceinline__ void attn_phase(const Args& a, LAS unsigned char* lds) {
;     ...
;             f32x4 s[2][4];
;             __builtin_amdgcn_s_setprio(1);
; #pragma unroll
;             for (int sub = 0; sub < 4; ++sub) {
;                 f32x4 a0 = (f32x4){0.f, 0.f, 0.f, 0.f}, a1 = a0;
; #pragma unroll
;                 for (int ks = 0; ks < NKS; ++ks) {
;                     const bf16x8 kf = *(const LAS bf16x8*)(Ks + (sub * 16 + r) * QST + ks * 32 + quad * 8);
;                     a0 = __builtin_amdgcn_mfma_f32_16x16x32_bf16(kf, qf[0][ks], a0, 0, 0, 0);
;                     a1 = __builtin_amdgcn_mfma_f32_16x16x32_bf16(kf, qf[1][ks], a1, 0, 0, 0);
;                 }
;                 s[0][sub] = a0; s[1][sub] = a1;
;             }
;             __builtin_amdgcn_s_setprio(0);
;             bf16x8 pf[2][2];
;             const bool need_mask = kt * 64 + 64 > nkw;
; #pragma unroll
;             for (int g = 0; g < 2; ++g) {
;                 f32x4 sv[4];
; #pragma unroll
;                 for (int sub = 0; sub < 4; ++sub) sv[sub] = s[g][sub] * scale;
;                 if (!MLA) {
; #pragma unroll
;                     for (int sub = 0; sub < 4; ++sub)
; #pragma unroll
;                         for (int jj = 0; jj < 4; ++jj) sv[sub][jj] += biasT[head * 256 + 191 + qi[g] - (kt * 64 + sub * 16 + quad * 4 + jj)];
;                 }
;                 if (need_mask) {
; #pragma unroll
;                     for (int sub = 0; sub < 4; ++sub)
; #pragma unroll
;                         for (int jj = 0; jj < 4; ++jj) if (kt * 64 + sub * 16 + quad * 4 + jj >= nkw) sv[sub][jj] = -INFINITY;
;                 }
.LBB0_863:
	s_bitcmp1_b32 s57, 0
	s_cselect_b32 s0, 0x4600, 0
	s_add_i32 s59, s0, 0
	v_add3_u32 v86, s59, v130, v95
	ds_read_b128 v[58:61], v86 offset:36864
	ds_read_b128 v[62:65], v86 offset:36928
	s_waitcnt lgkmcnt(1)
	v_mfma_f32_16x16x32_bf16 v[66:69], v[58:61], v[14:17], 0
	v_mfma_f32_16x16x32_bf16 v[58:61], v[58:61], v[6:9], 0
	s_waitcnt lgkmcnt(0)
	v_mfma_f32_16x16x32_bf16 v[74:77], v[62:65], v[10:13], v[66:69]
	v_mfma_f32_16x16x32_bf16 v[62:65], v[62:65], v[2:5], v[58:61]
	s_nop 4
	ds_read_b128 v[58:61], v86 offset:39168
	ds_read_b128 v[66:69], v86 offset:39232
	s_waitcnt lgkmcnt(1)
	v_mfma_f32_16x16x32_bf16 v[70:73], v[58:61], v[14:17], 0
	v_mfma_f32_16x16x32_bf16 v[58:61], v[58:61], v[6:9], 0
	s_waitcnt lgkmcnt(0)
	v_mfma_f32_16x16x32_bf16 v[78:81], v[66:69], v[10:13], v[70:73]
	v_mfma_f32_16x16x32_bf16 v[66:69], v[66:69], v[2:5], v[58:61]
	s_nop 4
	ds_read_b128 v[58:61], v86 offset:41472
	ds_read_b128 v[70:73], v86 offset:41536
	s_waitcnt lgkmcnt(1)
	v_mfma_f32_16x16x32_bf16 v[82:85], v[58:61], v[14:17], 0
	v_mfma_f32_16x16x32_bf16 v[58:61], v[58:61], v[6:9], 0
	s_waitcnt lgkmcnt(0)
	v_mfma_f32_16x16x32_bf16 v[82:85], v[70:73], v[10:13], v[82:85]
	v_mfma_f32_16x16x32_bf16 v[70:73], v[70:73], v[2:5], v[58:61]
	s_nop 4
	ds_read_b128 v[58:61], v86 offset:43776
	ds_read_b128 v[110:113], v86 offset:43840
	s_waitcnt lgkmcnt(1)
	v_mfma_f32_16x16x32_bf16 v[86:89], v[58:61], v[14:17], 0
	v_mfma_f32_16x16x32_bf16 v[58:61], v[58:61], v[6:9], 0
	s_waitcnt lgkmcnt(0)
	v_mfma_f32_16x16x32_bf16 v[58:61], v[110:113], v[2:5], v[58:61]
	v_mfma_f32_16x16x32_bf16 v[86:89], v[110:113], v[10:13], v[86:89]
	v_add_u32_e32 v116, s56, v101
	v_add_u32_e32 v110, 0xbf, v116
	v_readlane_b32 s0, v252, 16
	v_add_u32_e32 v112, 0xbe, v116
	v_ashrrev_i32_e32 v111, 31, v110
	v_readlane_b32 s1, v252, 17
	v_ashrrev_i32_e32 v113, 31, v112
	v_add_u32_e32 v114, 0xbc, v116
	v_lshl_add_u64 v[110:111], v[110:111], 2, s[0:1]
	v_lshl_add_u64 v[112:113], v[112:113], 2, s[0:1]
	global_load_dword v110, v[110:111], off
	v_ashrrev_i32_e32 v115, 31, v114
	global_load_dword v111, v[112:113], off
	v_add_u32_e32 v112, 0xbd, v116
	v_ashrrev_i32_e32 v113, 31, v112
	v_lshl_add_u64 v[112:113], v[112:113], 2, s[0:1]
	v_lshl_add_u64 v[114:115], v[114:115], 2, s[0:1]
	global_load_dword v112, v[112:113], off
	v_add_u32_e32 v144, s43, v131
	global_load_dword v113, v[114:115], off
	v_add_u32_e32 v114, 0xaf, v116
	v_ashrrev_i32_e32 v115, 31, v114
	v_lshl_add_u64 v[114:115], v[114:115], 2, s[0:1]
	global_load_dword v118, v[114:115], off
	v_add_u32_e32 v114, 0xae, v116
	v_ashrrev_i32_e32 v115, 31, v114
	v_lshl_add_u64 v[114:115], v[114:115], 2, s[0:1]
	global_load_dword v119, v[114:115], off
	v_add_u32_e32 v114, 0xad, v116
	v_ashrrev_i32_e32 v115, 31, v114
	v_lshl_add_u64 v[114:115], v[114:115], 2, s[0:1]
	global_load_dword v120, v[114:115], off
	v_add_u32_e32 v114, 0xac, v116
	v_ashrrev_i32_e32 v115, 31, v114
	v_lshl_add_u64 v[114:115], v[114:115], 2, s[0:1]
	global_load_dword v121, v[114:115], off
	v_add_u32_e32 v114, 0x9f, v116
	v_ashrrev_i32_e32 v115, 31, v114
	v_lshl_add_u64 v[114:115], v[114:115], 2, s[0:1]
	global_load_dword v160, v[114:115], off
	v_add_u32_e32 v114, 0x9e, v116
	v_ashrrev_i32_e32 v115, 31, v114
	v_lshl_add_u64 v[114:115], v[114:115], 2, s[0:1]
	global_load_dword v161, v[114:115], off
	v_add_u32_e32 v114, 0x9d, v116
	v_ashrrev_i32_e32 v115, 31, v114
	v_lshl_add_u64 v[114:115], v[114:115], 2, s[0:1]
	global_load_dword v162, v[114:115], off
	v_add_u32_e32 v114, 0x9c, v116
	v_ashrrev_i32_e32 v115, 31, v114
	v_lshl_add_u64 v[114:115], v[114:115], 2, s[0:1]
	global_load_dword v163, v[114:115], off
	v_add_u32_e32 v114, 0x8f, v116
	v_ashrrev_i32_e32 v115, 31, v114
	v_lshl_add_u64 v[114:115], v[114:115], 2, s[0:1]
	global_load_dword v164, v[114:115], off
	v_add_u32_e32 v114, 0x8e, v116
	v_ashrrev_i32_e32 v115, 31, v114
	v_lshl_add_u64 v[114:115], v[114:115], 2, s[0:1]
	global_load_dword v165, v[114:115], off
	v_add_u32_e32 v114, 0x8d, v116
	v_ashrrev_i32_e32 v115, 31, v114
	v_lshl_add_u64 v[114:115], v[114:115], 2, s[0:1]
	global_load_dword v166, v[114:115], off
	v_add_u32_e32 v114, 0x8c, v116
	v_ashrrev_i32_e32 v115, 31, v114
	v_lshl_add_u64 v[114:115], v[114:115], 2, s[0:1]
	global_load_dword v167, v[114:115], off
	s_cmp_gt_i32 s43, s54
	v_add_u32_e32 v145, 1, v144
	v_add_u32_e32 v146, 2, v144
	v_add_u32_e32 v147, 3, v144
	v_add_u32_e32 v148, 16, v144
	v_add_u32_e32 v149, 17, v144
	v_add_u32_e32 v150, 18, v144
	v_add_u32_e32 v151, 19, v144
	v_add_u32_e32 v152, 32, v144
	v_add_u32_e32 v153, 33, v144
	v_add_u32_e32 v154, 34, v144
	v_add_u32_e32 v155, 35, v144
	v_add_u32_e32 v156, 48, v144
	v_add_u32_e32 v157, 49, v144
	v_add_u32_e32 v158, 50, v144
	v_add_u32_e32 v159, 51, v144
	s_mov_b32 s0, 0x3e38aa3b
	s_cselect_b64 s[46:47], -1, 0
	s_cmp_le_i32 s43, s54
	v_cmp_gt_i32_e32 vcc, s53, v144
	v_cmp_gt_i32_e64 s[2:3], s53, v146
	v_cmp_gt_i32_e64 s[4:5], s53, v147
	v_cmp_gt_i32_e64 s[6:7], s53, v148
	v_cmp_gt_i32_e64 s[10:11], s53, v149
	s_waitcnt vmcnt(14)
	v_pk_fma_f32 v[116:117], v[74:75], s[0:1], v[110:111] op_sel_hi:[1,0,1]
	v_cmp_gt_i32_e64 s[12:13], s53, v150
	v_cmp_gt_i32_e64 s[14:15], s53, v151
	v_cmp_gt_i32_e64 s[16:17], s53, v152
	v_cmp_gt_i32_e64 s[18:19], s53, v153
	v_cmp_gt_i32_e64 s[20:21], s53, v154
	v_cmp_gt_i32_e64 s[22:23], s53, v155
	s_waitcnt vmcnt(12)
	v_pk_fma_f32 v[114:115], v[76:77], s[0:1], v[112:113] op_sel_hi:[1,0,1]
	v_cmp_gt_i32_e64 s[24:25], s53, v156
	v_cmp_gt_i32_e64 s[26:27], s53, v157
	v_cmp_gt_i32_e64 s[28:29], s53, v158
	v_cmp_gt_i32_e64 s[8:9], s53, v159
	s_waitcnt vmcnt(10)
	v_pk_fma_f32 v[112:113], v[78:79], s[0:1], v[118:119] op_sel_hi:[1,0,1]
	s_waitcnt vmcnt(8)
	v_pk_fma_f32 v[110:111], v[80:81], s[0:1], v[120:121] op_sel_hi:[1,0,1]
	s_waitcnt vmcnt(6)
	v_pk_fma_f32 v[78:79], v[82:83], s[0:1], v[160:161] op_sel_hi:[1,0,1]
	s_waitcnt vmcnt(4)
	v_pk_fma_f32 v[80:81], v[84:85], s[0:1], v[162:163] op_sel_hi:[1,0,1]
	s_waitcnt vmcnt(2)
	v_pk_fma_f32 v[76:77], v[86:87], s[0:1], v[164:165] op_sel_hi:[1,0,1]
	s_waitcnt vmcnt(0)
	v_pk_fma_f32 v[74:75], v[88:89], s[0:1], v[166:167] op_sel_hi:[1,0,1]
	v_cmp_gt_i32_e64 s[0:1], s53, v145
	s_cbranch_scc1 .LBB0_865
; template <bool MLA>
; __device__ __forceinline__ void attn_phase(const Args& a, LAS unsigned char* lds) {
;     ...
;                 if (need_mask) {
; #pragma unroll
;                     for (int sub = 0; sub < 4; ++sub)
; #pragma unroll
;                         for (int jj = 0; jj < 4; ++jj) if (kt * 64 + sub * 16 + quad * 4 + jj >= nkw) sv[sub][jj] = -INFINITY;
;                 }
	s_or_b64 s[28:29], s[8:9], s[28:29]
	s_or_b64 s[26:27], s[28:29], s[26:27]
	s_or_b64 s[24:25], s[26:27], s[24:25]
	s_or_b64 s[22:23], s[24:25], s[22:23]
	s_or_b64 s[20:21], s[22:23], s[20:21]
	s_or_b64 s[18:19], s[20:21], s[18:19]
	s_or_b64 s[16:17], s[18:19], s[16:17]
	s_or_b64 s[14:15], s[16:17], s[14:15]
	s_or_b64 s[12:13], s[14:15], s[12:13]
	s_or_b64 s[10:11], s[12:13], s[10:11]
	s_or_b64 s[6:7], s[10:11], s[6:7]
	s_or_b64 s[4:5], s[6:7], s[4:5]
	s_or_b64 s[2:3], s[4:5], s[2:3]
	s_or_b64 s[0:1], s[2:3], s[0:1]
	s_or_b64 vcc, s[0:1], vcc
	v_cndmask_b32_e64 v74, v245, v74, s[28:29]
	v_cndmask_b32_e64 v77, v245, v77, s[26:27]
	v_cndmask_b32_e64 v76, v245, v76, s[24:25]
	v_cndmask_b32_e64 v81, v245, v81, s[22:23]
	v_cndmask_b32_e64 v80, v245, v80, s[20:21]
	v_cndmask_b32_e64 v79, v245, v79, s[18:19]
	v_cndmask_b32_e64 v78, v245, v78, s[16:17]
	v_cndmask_b32_e64 v111, v245, v111, s[14:15]
	v_cndmask_b32_e64 v110, v245, v110, s[12:13]
	v_cndmask_b32_e64 v113, v245, v113, s[10:11]
	v_cndmask_b32_e64 v112, v245, v112, s[6:7]
	v_cndmask_b32_e64 v115, v245, v115, s[4:5]
	v_cndmask_b32_e64 v114, v245, v114, s[2:3]
	v_cndmask_b32_e64 v117, v245, v117, s[0:1]
	v_cndmask_b32_e32 v116, v245, v116, vcc
	v_cndmask_b32_e64 v75, v245, v75, s[8:9]
